# combine_pass: 9 serialized slab loads of the gate inputs issued together (one wait)
# baseline (speedup 1.0000x reference)
.LBB0_1197:
	v_min_i32_e32 v236, s4, v18
	v_add_u32_e32 v64, 1, v18
	v_add_u32_e32 v62, 2, v18
	v_min_i32_e32 v237, s4, v64
	v_min_i32_e32 v238, s4, v62
	global_load_dword v2, v[24:25], off offset:3328
	global_load_dword v3, v[26:27], off
	v_mad_i64_i32 v[4:5], s[6:7], v236, s24, v[22:23]
	v_cmp_gt_i32_e32 vcc, s93, v236
	global_load_ushort v240, v[4:5], off
	v_mov_b32_e32 v244, 0
	v_mov_b32_e32 v245, 0
	v_cndmask_b32_e32 v10, v252, v202, vcc
	v_cndmask_b32_e32 v11, v203, v202, vcc
	v_and_b32_e32 v10, v10, v236
	v_cmp_ne_u32_e64 s[44:45], 0, v10
	v_cmp_lt_u32_e32 vcc, v10, v11
	v_add_u32_e32 v8, -1, v236
	s_and_saveexec_b64 s[14:15], s[44:45]
	s_cbranch_execz .Lsg_a0
	v_mad_i64_i32 v[4:5], s[6:7], v8, s24, v[22:23]
	global_load_ushort v244, v[4:5], off
.Lsg_a0:
	s_or_b64 exec, exec, s[14:15]
	v_add_u32_e32 v8, 1, v236
	s_and_saveexec_b64 s[14:15], vcc
	s_cbranch_execz .Lsg_b0
	v_mad_i64_i32 v[4:5], s[6:7], v8, s24, v[22:23]
	global_load_ushort v245, v[4:5], off
.Lsg_b0:
	s_or_b64 exec, exec, s[14:15]
	v_mad_i64_i32 v[4:5], s[6:7], v237, s24, v[22:23]
	v_cmp_gt_i32_e32 vcc, s93, v237
	global_load_ushort v241, v[4:5], off
	v_mov_b32_e32 v246, 0
	v_mov_b32_e32 v247, 0
	v_cndmask_b32_e32 v10, v252, v202, vcc
	v_cndmask_b32_e32 v11, v203, v202, vcc
	v_and_b32_e32 v10, v10, v237
	v_cmp_ne_u32_e64 s[44:45], 0, v10
	v_cmp_lt_u32_e32 vcc, v10, v11
	v_add_u32_e32 v8, -1, v237
	s_and_saveexec_b64 s[14:15], s[44:45]
	s_cbranch_execz .Lsg_a1
	v_mad_i64_i32 v[4:5], s[6:7], v8, s24, v[22:23]
	global_load_ushort v246, v[4:5], off
.Lsg_a1:
	s_or_b64 exec, exec, s[14:15]
	v_add_u32_e32 v8, 1, v237
	s_and_saveexec_b64 s[14:15], vcc
	s_cbranch_execz .Lsg_b1
	v_mad_i64_i32 v[4:5], s[6:7], v8, s24, v[22:23]
	global_load_ushort v247, v[4:5], off
.Lsg_b1:
	s_or_b64 exec, exec, s[14:15]
	v_mad_i64_i32 v[4:5], s[6:7], v238, s24, v[22:23]
	v_cmp_gt_i32_e32 vcc, s93, v238
	global_load_ushort v242, v[4:5], off
	v_mov_b32_e32 v248, 0
	v_mov_b32_e32 v249, 0
	v_cndmask_b32_e32 v10, v252, v202, vcc
	v_cndmask_b32_e32 v11, v203, v202, vcc
	v_and_b32_e32 v10, v10, v238
	v_cmp_ne_u32_e64 s[44:45], 0, v10
	v_cmp_lt_u32_e32 vcc, v10, v11
	v_add_u32_e32 v8, -1, v238
	s_and_saveexec_b64 s[14:15], s[44:45]
	s_cbranch_execz .Lsg_a2
	v_mad_i64_i32 v[4:5], s[6:7], v8, s24, v[22:23]
	global_load_ushort v248, v[4:5], off
.Lsg_a2:
	s_or_b64 exec, exec, s[14:15]
	v_add_u32_e32 v8, 1, v238
	s_and_saveexec_b64 s[14:15], vcc
	s_cbranch_execz .Lsg_b2
	v_mad_i64_i32 v[4:5], s[6:7], v8, s24, v[22:23]
	global_load_ushort v249, v[4:5], off
.Lsg_b2:
	s_or_b64 exec, exec, s[14:15]
	s_waitcnt vmcnt(0)
	v_lshlrev_b32_e32 v244, 16, v244
	v_lshlrev_b32_e32 v245, 16, v245
	v_lshlrev_b32_e32 v0, 16, v240
	v_pk_add_f32 v[4:5], v[244:245], v[0:1] op_sel_hi:[1,0] neg_lo:[0,1] neg_hi:[0,1]
	v_pk_mul_f32 v[4:5], v[2:3], v[4:5]
	s_nop 0
	v_add_f32_e32 v0, v4, v0
	v_add_f32_e32 v0, v0, v5
	v_mul_f32_e32 v0, 0xbfb8aa3b, v0
	v_exp_f32_e32 v0, v0
	s_nop 0
	v_add_f32_e32 v0, 1.0, v0
	v_rcp_f32_e32 v0, v0
	s_nop 0
	ds_write_b32 v21, v0
	v_lshlrev_b32_e32 v246, 16, v246
	v_lshlrev_b32_e32 v247, 16, v247
	v_lshlrev_b32_e32 v0, 16, v241
	v_pk_add_f32 v[4:5], v[246:247], v[0:1] op_sel_hi:[1,0] neg_lo:[0,1] neg_hi:[0,1]
	v_pk_mul_f32 v[4:5], v[2:3], v[4:5]
	s_nop 0
	v_add_f32_e32 v0, v4, v0
	v_add_f32_e32 v0, v0, v5
	v_mul_f32_e32 v0, 0xbfb8aa3b, v0
	v_exp_f32_e32 v0, v0
	s_nop 0
	v_add_f32_e32 v0, 1.0, v0
	v_rcp_f32_e32 v0, v0
	s_nop 0
	ds_write_b32 v21, v0 offset:256
	v_lshlrev_b32_e32 v248, 16, v248
	v_lshlrev_b32_e32 v249, 16, v249
	v_lshlrev_b32_e32 v0, 16, v242
	v_pk_add_f32 v[4:5], v[248:249], v[0:1] op_sel_hi:[1,0] neg_lo:[0,1] neg_hi:[0,1]
	v_pk_mul_f32 v[4:5], v[2:3], v[4:5]
	s_nop 0
	v_add_f32_e32 v0, v4, v0
	v_add_f32_e32 v0, v0, v5
	v_mul_f32_e32 v0, 0xbfb8aa3b, v0
	v_exp_f32_e32 v0, v0
	s_nop 0
	v_add_f32_e32 v0, 1.0, v0
	v_rcp_f32_e32 v0, v0
	s_nop 0
	ds_write_b32 v21, v0 offset:512
	v_mov_b32_e32 v58, 0
	s_mov_b32 s6, 0
	v_mov_b64_e32 v[2:3], v[56:57]
	v_mov_b32_e32 v59, v58
	v_mov_b32_e32 v60, v58
	v_mov_b32_e32 v61, v58
	v_mov_b32_e32 v68, v58
	v_mov_b32_e32 v69, v58
	v_mov_b32_e32 v70, v58
	v_mov_b32_e32 v71, v58
	v_mov_b32_e32 v74, v58
	v_mov_b32_e32 v75, v58
	v_mov_b32_e32 v76, v58
	v_mov_b32_e32 v77, v58
